# P10: first 20 loads of a unit (logf, q) requested one unit ahead; the 20 scattered S^T/v/gate loads spread over four later points of the unit instead of queued at its top (same VMEM order, counted wai
# speedup vs baseline: 1.0441x; 1.0125x over previous
.LBB0_976:
	s_or_b64 exec, exec, s[4:5]
	s_add_u32 s58, s84, 0x9b00000
	s_addc_u32 s59, s85, 0
	v_mov_b32_e32 v0, v191
	s_and_b64 vcc, exec, s[0:1]
	s_waitcnt lgkmcnt(0)
	s_barrier
	s_cbranch_vccz .LBB0_993
	v_ashrrev_i32_e32 v1, 6, v0
	v_lshlrev_b32_e32 v3, 3, v0
	v_and_b32_e32 v3, 0x78, v3
	v_bfe_u32 v5, v0, 4, 2
	v_lshlrev_b32_e32 v4, 3, v1
	v_ashrrev_i32_e32 v9, 7, v0
	v_mov_b32_e32 v97, 0
	v_lshlrev_b32_e32 v96, 1, v3
	v_and_b32_e32 v100, 15, v0
	v_bfi_b32 v109, -16, v4, v0
	v_lshlrev_b32_e32 v4, 2, v5
	v_lshlrev_b32_e32 v111, 4, v9
	v_lshl_add_u64 v[98:99], s[14:15], 0, v[96:97]
	v_lshlrev_b32_e32 v8, 3, v5
	v_lshlrev_b32_e32 v96, 4, v5
	v_or_b32_e32 v135, v111, v100
	v_cmp_eq_u32_e64 s[12:13], 0, v5
	v_or_b32_e32 v5, 2, v4
	v_cmp_gt_i32_e64 s[20:21], v5, v135
	v_or_b32_e32 v5, 3, v4
	v_cmp_gt_i32_e64 s[22:23], v5, v135
	v_or_b32_e32 v5, 16, v4
	v_cmp_gt_i32_e64 s[24:25], v5, v135
	v_or_b32_e32 v5, 17, v4
	v_lshlrev_b32_e32 v2, 4, v0
	v_lshlrev_b32_e32 v10, 2, v0
	v_cmp_gt_i32_e64 s[26:27], v5, v135
	v_or_b32_e32 v5, 18, v4
	v_ashrrev_i32_e32 v101, 3, v0
	v_and_b32_e32 v2, 0x70, v2
	v_lshl_add_u64 v[102:103], s[28:29], 0, v[96:97]
	v_and_b32_e32 v6, 0x1fc, v10
	v_mov_b32_e32 v7, v97
	v_cmp_gt_i32_e64 s[28:29], v5, v135
	v_or_b32_e32 v5, 19, v4
	v_lshl_add_u64 v[104:105], s[30:31], 0, v[6:7]
	v_add_u32_e32 v128, 16, v6
	v_max_i32_e32 v6, 1, v101
	s_movk_i32 s3, 0x210
	v_lshlrev_b32_e32 v12, 2, v2
	v_cmp_gt_i32_e64 s[30:31], v5, v135
	v_or_b32_e32 v5, 32, v4
	v_mul_lo_u32 v11, v101, s3
	v_mul_lo_u32 v6, v6, s3
	v_add_u32_e32 v130, 16, v12
	s_movk_i32 s0, 0xfdf0
	v_cmp_gt_i32_e64 s[34:35], v5, v135
	v_or_b32_e32 v5, 33, v4
	v_add_u32_e32 v11, 16, v11
	v_add3_u32 v131, v130, v6, s0
	v_lshlrev_b32_e32 v6, 8, v101
	v_cmp_gt_i32_e64 s[36:37], v5, v135
	v_or_b32_e32 v5, 34, v4
	s_add_u32 s62, s84, 0x19b00000
	v_add_u32_e32 v129, v11, v12
	v_sub_u32_e32 v6, v11, v6
	v_lshlrev_b32_e32 v11, 1, v2
	s_movk_i32 s16, 0x110
	v_cmp_gt_i32_e64 s[38:39], v5, v135
	v_or_b32_e32 v5, 35, v4
	s_addc_u32 s63, s85, 0
	v_add_u32_e32 v132, v6, v11
	s_add_i32 s0, 16, 0x12800
	v_mul_lo_u32 v6, v101, s16
	s_add_i32 s1, 16, 0x16c00
	v_cmp_gt_i32_e64 s[40:41], v5, v135
	v_or_b32_e32 v5, 48, v4
	v_add3_u32 v133, s0, v6, v11
	v_add3_u32 v134, s1, v6, v11
	v_and_b32_e32 v1, 1, v1
	v_mul_lo_u32 v6, v135, s16
	v_cmp_gt_i32_e64 s[42:43], v5, v135
	v_or_b32_e32 v5, 49, v4
	v_add3_u32 v136, s0, v6, v96
	v_add3_u32 v137, s1, v6, v96
	v_lshlrev_b32_e32 v6, 6, v1
	v_cmp_lt_i32_e64 s[0:1], v197, v195
	v_lshl_add_u32 v140, v135, 3, 16
	v_cmp_gt_i32_e64 s[44:45], v5, v135
	v_or_b32_e32 v5, 50, v4
	v_ashrrev_i32_e32 v107, 4, v0
	v_and_b32_e32 v7, 0xffffff0, v101
	v_add_u32_e32 v11, 16, v96
	v_or_b32_e32 v12, v6, v100
	v_cndmask_b32_e64 v13, v193, v197, s[0:1]
	v_cmp_lt_i32_e64 s[0:1], v206, v195
	v_lshl_add_u32 v141, v1, 2, v140
	v_or_b32_e32 v6, v6, v4
	v_or_b32_e32 v1, 15, v101
	v_cmp_gt_i32_e64 s[46:47], v5, v135
	v_or_b32_e32 v5, 51, v4
	v_add_u32_e32 v113, 16, v10
	v_lshl_add_u32 v10, v107, 1, 16
	v_sub_u32_e32 v8, v11, v8
	v_lshlrev_b32_e32 v138, 2, v13
	v_cndmask_b32_e64 v13, v193, v206, s[0:1]
	v_and_b32_e32 v106, 64, v0
	v_mul_lo_u32 v0, v7, s3
	v_mul_lo_u32 v1, v1, s3
	v_mul_u32_u24_e32 v3, 0x90, v3
	v_mad_u32_u24 v142, v100, s16, v11
	v_cmp_gt_i32_e64 s[48:49], v5, v135
	v_mul_u32_u24_e32 v5, 0x90, v12
	v_lshlrev_b32_e32 v96, 2, v6
	s_mov_b32 s69, 0
	v_cmp_lt_i32_e32 vcc, 0, v9
	v_cmp_lt_i32_e64 s[4:5], 1, v9
	v_cmp_lt_i32_e64 s[6:7], 2, v9
	v_cmp_lt_i32_e64 s[8:9], 3, v9
	v_cmp_lt_i32_e64 s[10:11], 0, v101
	v_lshlrev_b32_e32 v139, 2, v13
	v_or_b32_e32 v108, 16, v106
	v_or_b32_e32 v110, 32, v106
	v_or_b32_e32 v112, 48, v106
	v_cmp_lt_i32_e64 s[14:15], -1, v9
	v_add_u32_e32 v143, 0xe400, v142
	v_cmp_gt_i32_e64 s[16:17], v4, v135
	v_cmp_lt_i32_e64 s[18:19], v4, v135
	v_lshl_add_u64 v[114:115], s[60:61], 0, v[96:97]
	s_lshl_b32 s55, s2, 6
	s_lshl_b32 s70, s86, 6
	v_lshlrev_b32_e32 v96, 1, v2
	s_mov_b32 s71, 0x10000
	v_lshlrev_b32_e32 v116, 1, v4
	v_add_u32_e32 v144, v128, v0
	v_add_u32_e32 v145, v128, v1
	v_add_u32_e32 v146, v10, v3
	v_mov_b32_e32 v147, 0x358637bd
	s_mov_b32 s72, 0x800000
	v_lshlrev_b32_e32 v118, 1, v6
	v_add_u32_e32 v148, v8, v5
	s_mov_b32 s73, s97
	s_and_b32 s0, s73, 0xffffc000
	s_and_b32 s1, s55, 0x3fc0
	s_or_b32 s74, s0, s1
	s_lshr_b32 s0, s2, 1
	s_and_b32 s0, s0, 0x380
	s_lshl_b32 s60, s0, 2
	s_mov_b32 s61, s69
	s_lshl_b32 s68, s0, 1
	v_add_u32_e32 v2, s74, v111
	v_ashrrev_i32_e32 v3, 31, v2
	v_or_b32_e32 v8, 1, v2
	v_or_b32_e32 v10, 2, v2
	v_or_b32_e32 v12, 3, v2
	v_or_b32_e32 v14, 4, v2
	v_or_b32_e32 v16, 5, v2
	v_or_b32_e32 v18, 6, v2
	v_or_b32_e32 v20, 7, v2
	v_lshl_add_u64 v[4:5], v[104:105], 0, s[60:61]
	v_lshlrev_b64 v[6:7], 12, v[2:3]
	v_ashrrev_i32_e32 v9, 31, v8
	v_ashrrev_i32_e32 v11, 31, v10
	v_ashrrev_i32_e32 v13, 31, v12
	v_ashrrev_i32_e32 v15, 31, v14
	v_ashrrev_i32_e32 v17, 31, v16
	v_ashrrev_i32_e32 v19, 31, v18
	v_ashrrev_i32_e32 v21, 31, v20
	v_lshl_add_u64 v[6:7], v[4:5], 0, v[6:7]
	v_lshlrev_b64 v[8:9], 12, v[8:9]
	v_lshlrev_b64 v[10:11], 12, v[10:11]
	v_lshlrev_b64 v[12:13], 12, v[12:13]
	v_lshlrev_b64 v[14:15], 12, v[14:15]
	v_lshlrev_b64 v[16:17], 12, v[16:17]
	v_lshlrev_b64 v[18:19], 12, v[18:19]
	v_lshlrev_b64 v[20:21], 12, v[20:21]
	v_lshl_add_u64 v[8:9], v[4:5], 0, v[8:9]
	v_lshl_add_u64 v[10:11], v[4:5], 0, v[10:11]
	v_lshl_add_u64 v[12:13], v[4:5], 0, v[12:13]
	v_lshl_add_u64 v[14:15], v[4:5], 0, v[14:15]
	v_lshl_add_u64 v[16:17], v[4:5], 0, v[16:17]
	v_lshl_add_u64 v[18:19], v[4:5], 0, v[18:19]
	v_lshl_add_u64 v[20:21], v[4:5], 0, v[20:21]
	global_load_dword v216, v[6:7], off
	global_load_dword v217, v[8:9], off
	global_load_dword v218, v[10:11], off
	global_load_dword v219, v[12:13], off
	global_load_dword v220, v[14:15], off
	global_load_dword v221, v[16:17], off
	global_load_dword v222, v[18:19], off
	global_load_dword v223, v[20:21], off
	v_or_b32_e32 v6, 8, v2
	v_ashrrev_i32_e32 v7, 31, v6
	v_or_b32_e32 v8, 9, v2
	v_or_b32_e32 v10, 10, v2
	v_or_b32_e32 v12, 11, v2
	v_or_b32_e32 v14, 12, v2
	v_or_b32_e32 v16, 13, v2
	v_or_b32_e32 v18, 14, v2
	v_or_b32_e32 v2, 15, v2
	v_lshlrev_b64 v[6:7], 12, v[6:7]
	v_ashrrev_i32_e32 v9, 31, v8
	v_ashrrev_i32_e32 v11, 31, v10
	v_ashrrev_i32_e32 v13, 31, v12
	v_ashrrev_i32_e32 v15, 31, v14
	v_ashrrev_i32_e32 v17, 31, v16
	v_ashrrev_i32_e32 v19, 31, v18
	v_ashrrev_i32_e32 v3, 31, v2
	v_lshl_add_u64 v[6:7], v[4:5], 0, v[6:7]
	v_lshlrev_b64 v[8:9], 12, v[8:9]
	v_lshlrev_b64 v[10:11], 12, v[10:11]
	v_lshlrev_b64 v[12:13], 12, v[12:13]
	v_lshlrev_b64 v[14:15], 12, v[14:15]
	v_lshlrev_b64 v[16:17], 12, v[16:17]
	v_lshlrev_b64 v[18:19], 12, v[18:19]
	v_lshlrev_b64 v[2:3], 12, v[2:3]
	v_lshl_add_u64 v[8:9], v[4:5], 0, v[8:9]
	v_lshl_add_u64 v[10:11], v[4:5], 0, v[10:11]
	v_lshl_add_u64 v[12:13], v[4:5], 0, v[12:13]
	v_lshl_add_u64 v[14:15], v[4:5], 0, v[14:15]
	v_lshl_add_u64 v[16:17], v[4:5], 0, v[16:17]
	v_lshl_add_u64 v[18:19], v[4:5], 0, v[18:19]
	v_lshl_add_u64 v[2:3], v[4:5], 0, v[2:3]
	global_load_dword v224, v[6:7], off
	global_load_dword v225, v[8:9], off
	global_load_dword v226, v[10:11], off
	global_load_dword v227, v[12:13], off
	global_load_dword v228, v[14:15], off
	global_load_dword v229, v[16:17], off
	global_load_dword v230, v[18:19], off
	global_load_dword v231, v[2:3], off
	v_add_u32_e32 v0, s74, v101
	v_ashrrev_i32_e32 v1, 31, v0
	v_lshlrev_b64 v[0:1], 11, v[0:1]
	v_lshl_add_u64 v[0:1], s[58:59], 0, v[0:1]
	v_lshl_add_u64 v[0:1], v[0:1], 0, s[68:69]
	v_lshl_add_u64 v[0:1], v[0:1], 0, v[96:97]
	global_load_dwordx4 v[232:235], v[0:1], off offset:16
	global_load_dwordx4 v[236:239], v[0:1], off
	v_add_u32_e32 v0, s74, v107
	v_ashrrev_i32_e32 v1, 31, v0
	v_lshl_add_u64 v[2:3], v[98:99], 0, s[68:69]
	v_lshlrev_b64 v[0:1], 11, v[0:1]
	v_lshl_add_u64 v[0:1], v[2:3], 0, v[0:1]
	v_add_co_u32_e64 v2, s[98:99], s71, v0
	s_nop 0
	s_nop 0
	v_addc_co_u32_e64 v3, s[98:99], 0, v1, s[98:99]
	global_load_dwordx4 v[240:243], v[0:1], off
	global_load_dwordx4 v[244:247], v[2:3], off
	s_waitcnt vmcnt(0)
	s_branch .LBB0_979

.LBB0_979:
	s_waitcnt vmcnt(1)
	v_mov_b32_e32 v78, v216
	v_mov_b32_e32 v79, v217
	v_mov_b32_e32 v84, v218
	v_mov_b32_e32 v85, v219
	v_mov_b32_e32 v86, v220
	v_mov_b32_e32 v87, v221
	v_mov_b32_e32 v88, v222
	v_mov_b32_e32 v89, v223
	v_mov_b32_e32 v90, v224
	v_mov_b32_e32 v91, v225
	v_mov_b32_e32 v92, v226
	v_mov_b32_e32 v93, v227
	v_mov_b32_e32 v94, v228
	v_mov_b32_e32 v95, v229
	v_mov_b32_e32 v119, v230
	v_mov_b32_e32 v149, v231
	v_mov_b64_e32 v[64:65], v[232:233]
	v_mov_b64_e32 v[66:67], v[234:235]
	v_mov_b64_e32 v[80:81], v[236:237]
	v_mov_b64_e32 v[82:83], v[238:239]
	v_mov_b64_e32 v[68:69], v[240:241]
	v_mov_b64_e32 v[70:71], v[242:243]
	v_mov_b64_e32 v[72:73], v[244:245]
	v_mov_b64_e32 v[74:75], v[246:247]
	s_and_b32 s0, s73, 0xffffc000
	s_and_b32 s1, s55, 0x3fc0
	s_or_b32 s74, s0, s1
	s_lshr_b32 s0, s2, 1
	s_and_b32 s0, s0, 0x380
	s_lshl_b32 s60, s0, 2
	s_mov_b32 s61, s69
	s_lshl_b32 s68, s0, 1
	v_mov_b32_e32 v117, v97
	s_add_i32 s91, s2, s86
	s_add_i32 s100, s73, s54
	s_add_i32 s101, s55, s70
	s_cmpk_gt_i32 s91, 0xfff
	s_cselect_b32 s91, s2, s91
	s_cselect_b32 s100, s73, s100
	s_cselect_b32 s101, s55, s101
	s_and_b32 s90, s100, 0xffffc000
	s_and_b32 s92, s101, 0x3fc0
	s_or_b32 s90, s90, s92
	s_lshr_b32 s91, s91, 1
	s_and_b32 s91, s91, 0x380
	s_lshl_b32 s92, s91, 2
	s_mov_b32 s93, s69
	s_lshl_b32 s94, s91, 1
	s_mov_b32 s95, s69
	v_add_u32_e32 v2, s90, v111
	v_ashrrev_i32_e32 v3, 31, v2
	v_or_b32_e32 v8, 1, v2
	v_or_b32_e32 v10, 2, v2
	v_or_b32_e32 v12, 3, v2
	v_or_b32_e32 v14, 4, v2
	v_or_b32_e32 v16, 5, v2
	v_or_b32_e32 v18, 6, v2
	v_or_b32_e32 v20, 7, v2
	v_lshl_add_u64 v[4:5], v[104:105], 0, s[92:93]
	v_lshlrev_b64 v[6:7], 12, v[2:3]
	v_ashrrev_i32_e32 v9, 31, v8
	v_ashrrev_i32_e32 v11, 31, v10
	v_ashrrev_i32_e32 v13, 31, v12
	v_ashrrev_i32_e32 v15, 31, v14
	v_ashrrev_i32_e32 v17, 31, v16
	v_ashrrev_i32_e32 v19, 31, v18
	v_ashrrev_i32_e32 v21, 31, v20
	v_lshl_add_u64 v[6:7], v[4:5], 0, v[6:7]
	v_lshlrev_b64 v[8:9], 12, v[8:9]
	v_lshlrev_b64 v[10:11], 12, v[10:11]
	v_lshlrev_b64 v[12:13], 12, v[12:13]
	v_lshlrev_b64 v[14:15], 12, v[14:15]
	v_lshlrev_b64 v[16:17], 12, v[16:17]
	v_lshlrev_b64 v[18:19], 12, v[18:19]
	v_lshlrev_b64 v[20:21], 12, v[20:21]
	v_lshl_add_u64 v[8:9], v[4:5], 0, v[8:9]
	v_lshl_add_u64 v[10:11], v[4:5], 0, v[10:11]
	v_lshl_add_u64 v[12:13], v[4:5], 0, v[12:13]
	v_lshl_add_u64 v[14:15], v[4:5], 0, v[14:15]
	v_lshl_add_u64 v[16:17], v[4:5], 0, v[16:17]
	v_lshl_add_u64 v[18:19], v[4:5], 0, v[18:19]
	v_lshl_add_u64 v[20:21], v[4:5], 0, v[20:21]
	global_load_dword v216, v[6:7], off
	global_load_dword v217, v[8:9], off
	global_load_dword v218, v[10:11], off
	global_load_dword v219, v[12:13], off
	global_load_dword v220, v[14:15], off
	global_load_dword v221, v[16:17], off
	global_load_dword v222, v[18:19], off
	global_load_dword v223, v[20:21], off
	v_or_b32_e32 v6, 8, v2
	v_ashrrev_i32_e32 v7, 31, v6
	v_or_b32_e32 v8, 9, v2
	v_or_b32_e32 v10, 10, v2
	v_or_b32_e32 v12, 11, v2
	v_or_b32_e32 v14, 12, v2
	v_or_b32_e32 v16, 13, v2
	v_or_b32_e32 v18, 14, v2
	v_or_b32_e32 v2, 15, v2
	v_lshlrev_b64 v[6:7], 12, v[6:7]
	v_ashrrev_i32_e32 v9, 31, v8
	v_ashrrev_i32_e32 v11, 31, v10
	v_ashrrev_i32_e32 v13, 31, v12
	v_ashrrev_i32_e32 v15, 31, v14
	v_ashrrev_i32_e32 v17, 31, v16
	v_ashrrev_i32_e32 v19, 31, v18
	v_ashrrev_i32_e32 v3, 31, v2
	v_lshl_add_u64 v[6:7], v[4:5], 0, v[6:7]
	v_lshlrev_b64 v[8:9], 12, v[8:9]
	v_lshlrev_b64 v[10:11], 12, v[10:11]
	v_lshlrev_b64 v[12:13], 12, v[12:13]
	v_lshlrev_b64 v[14:15], 12, v[14:15]
	v_lshlrev_b64 v[16:17], 12, v[16:17]
	v_lshlrev_b64 v[18:19], 12, v[18:19]
	v_lshlrev_b64 v[2:3], 12, v[2:3]
	v_lshl_add_u64 v[8:9], v[4:5], 0, v[8:9]
	v_lshl_add_u64 v[10:11], v[4:5], 0, v[10:11]
	v_lshl_add_u64 v[12:13], v[4:5], 0, v[12:13]
	v_lshl_add_u64 v[14:15], v[4:5], 0, v[14:15]
	v_lshl_add_u64 v[16:17], v[4:5], 0, v[16:17]
	v_lshl_add_u64 v[18:19], v[4:5], 0, v[18:19]
	v_lshl_add_u64 v[2:3], v[4:5], 0, v[2:3]
	global_load_dword v224, v[6:7], off
	global_load_dword v225, v[8:9], off
	global_load_dword v226, v[10:11], off
	global_load_dword v227, v[12:13], off
	global_load_dword v228, v[14:15], off
	global_load_dword v229, v[16:17], off
	global_load_dword v230, v[18:19], off
	global_load_dword v231, v[2:3], off
	v_add_u32_e32 v0, s90, v101
	v_ashrrev_i32_e32 v1, 31, v0
	v_lshlrev_b64 v[0:1], 11, v[0:1]
	v_lshl_add_u64 v[0:1], s[58:59], 0, v[0:1]
	v_lshl_add_u64 v[0:1], v[0:1], 0, s[94:95]
	v_lshl_add_u64 v[0:1], v[0:1], 0, v[96:97]
	global_load_dwordx4 v[232:235], v[0:1], off offset:16
	global_load_dwordx4 v[236:239], v[0:1], off
	v_add_u32_e32 v0, s90, v107
	v_ashrrev_i32_e32 v1, 31, v0
	v_lshl_add_u64 v[2:3], v[98:99], 0, s[94:95]
	v_lshlrev_b64 v[0:1], 11, v[0:1]
	v_lshl_add_u64 v[0:1], v[2:3], 0, v[0:1]
	v_add_co_u32_e64 v2, s[98:99], s71, v0
	s_nop 0
	s_nop 0
	v_addc_co_u32_e64 v3, s[98:99], 0, v1, s[98:99]
	global_load_dwordx4 v[240:243], v[0:1], off
	global_load_dwordx4 v[244:247], v[2:3], off
	v_add_f32_e32 v117, 0, v78
	v_add_f32_e32 v150, v117, v79
	v_add_f32_e32 v84, v150, v84
	v_add_f32_e32 v85, v84, v85
	v_add_f32_e32 v86, v85, v86
	v_add_f32_e32 v87, v86, v87
	v_add_f32_e32 v88, v87, v88
	v_add_f32_e32 v89, v88, v89
	v_add_f32_e32 v90, v89, v90
	v_add_f32_e32 v91, v90, v91
	v_add_f32_e32 v92, v91, v92
	v_add_f32_e32 v93, v92, v93
	v_add_f32_e32 v94, v93, v94
	v_add_f32_e32 v95, v94, v95
	v_add_f32_e32 v119, v95, v119
	v_add_f32_e32 v149, v119, v149
	ds_write_b32 v113, v149 offset:53248
	s_waitcnt lgkmcnt(0)
	s_barrier
	s_mov_b32 s100, s2
	v_mov_b32_e32 v182, v116
	v_mov_b32_e32 v183, v97
	v_add_u32_e32 v0, s74, v109
	v_ashrrev_i32_e32 v1, 31, v0
	v_lshlrev_b64 v[0:1], 11, v[0:1]
	v_lshl_add_u64 v[0:1], s[62:63], 0, v[0:1]
	v_lshl_add_u64 v[0:1], v[0:1], 0, s[68:69]
	s_ashr_i32 s101, s2, 31
	v_lshl_add_u64 v[0:1], v[0:1], 0, v[182:183]
	s_lshl_b64 s[98:99], s[100:101], 7
	v_or_b32_e32 v4, s98, v100
	v_mov_b32_e32 v3, s99
	v_or_b32_e32 v2, v4, v106
	v_lshlrev_b64 v[2:3], 8, v[2:3]
	v_lshl_add_u64 v[2:3], v[102:103], 0, v[2:3]
	global_load_dwordx4 v[8:11], v[2:3], off
	global_load_dwordx4 v[12:15], v[2:3], off offset:64
	global_load_dwordx4 v[16:19], v[2:3], off offset:128
	global_load_dwordx4 v[20:23], v[2:3], off offset:192
	v_lshlrev_b32_e32 v2, 1, v106
	v_mov_b32_e32 v3, v97
	v_lshl_add_u64 v[180:181], v[0:1], 0, v[2:3]
	ds_read2st64_b32 v[76:77], v128 offset0:208 offset1:210
	ds_read2st64_b32 v[78:79], v128 offset0:212 offset1:214
	s_waitcnt lgkmcnt(1)
	v_add_f32_e32 v76, 0, v76
	v_cndmask_b32_e32 v76, 0, v76, vcc
	v_add_f32_e32 v77, v77, v76
	v_cndmask_b32_e64 v76, v76, v77, s[4:5]
	s_waitcnt lgkmcnt(0)
	v_add_f32_e32 v77, v78, v76
	v_cndmask_b32_e64 v76, v76, v77, s[6:7]
	v_add_f32_e32 v77, v79, v76
	v_cndmask_b32_e64 v76, v76, v77, s[8:9]
	v_add_f32_e32 v77, v117, v76
	v_add_f32_e32 v78, v150, v76
	v_add_f32_e32 v79, v84, v76
	v_add_f32_e32 v84, v85, v76
	ds_write2_b32 v144, v77, v78 offset1:132
	v_add_u32_e32 v77, 0x400, v144
	v_add_f32_e32 v85, v86, v76
	v_add_f32_e32 v86, v87, v76
	ds_write2_b32 v77, v79, v84 offset0:8 offset1:140
	v_add_u32_e32 v77, 0x800, v144
	v_add_f32_e32 v87, v88, v76
	v_add_f32_e32 v88, v89, v76
	ds_write2_b32 v77, v85, v86 offset0:16 offset1:148
	v_add_u32_e32 v77, 0xc00, v144
	v_add_f32_e32 v89, v90, v76
	v_add_f32_e32 v90, v91, v76
	ds_write2_b32 v77, v87, v88 offset0:24 offset1:156
	v_add_u32_e32 v77, 0x1000, v144
	v_add_f32_e32 v91, v92, v76
	v_add_f32_e32 v92, v93, v76
	ds_write2_b32 v77, v89, v90 offset0:32 offset1:164
	v_add_u32_e32 v77, 0x1400, v144
	v_add_f32_e32 v93, v94, v76
	v_add_f32_e32 v94, v95, v76
	v_add_f32_e32 v95, v119, v76
	v_add_f32_e32 v76, v149, v76
	ds_write2_b32 v77, v91, v92 offset0:40 offset1:172
	v_add_u32_e32 v77, 0x1800, v144
	ds_write2_b32 v77, v93, v94 offset0:48 offset1:180
	ds_write_b32 v144, v95 offset:7392
	ds_write_b32 v145, v76
	ds_write_b16 v146, v68 offset:34816
	ds_write_b16_d16_hi v146, v68 offset:34960
	ds_write_b16 v146, v69 offset:35104
	ds_write_b16_d16_hi v146, v69 offset:35248
	ds_write_b16 v146, v70 offset:35392
	ds_write_b16_d16_hi v146, v70 offset:35536
	ds_write_b16 v146, v71 offset:35680
	ds_write_b16_d16_hi v146, v71 offset:35824
	ds_write_b16 v146, v72 offset:34880
	ds_write_b16_d16_hi v146, v72 offset:35024
	ds_write_b16 v146, v73 offset:35168
	ds_write_b16_d16_hi v146, v73 offset:35312
	ds_write_b16 v146, v74 offset:35456
	ds_write_b16_d16_hi v146, v74 offset:35600
	ds_write_b16 v146, v75 offset:35744
	ds_write_b16_d16_hi v146, v75 offset:35888
	s_waitcnt lgkmcnt(0)
	s_barrier
	v_mov_b32_e32 v1, s99
	v_or_b32_e32 v0, v4, v108
	v_lshlrev_b64 v[0:1], 8, v[0:1]
	v_lshl_add_u64 v[0:1], v[102:103], 0, v[0:1]
	global_load_dwordx4 v[32:35], v[0:1], off
	global_load_dwordx4 v[36:39], v[0:1], off offset:64
	global_load_dwordx4 v[40:43], v[0:1], off offset:128
	global_load_dwordx4 v[44:47], v[0:1], off offset:192
	ds_read_b128 v[88:91], v129
	ds_read_b128 v[150:153], v129 offset:16
	ds_read_b128 v[154:157], v129 offset:32
	ds_read_b128 v[68:71], v129 offset:48
	ds_read_b128 v[92:95], v131
	ds_read_b128 v[158:161], v131 offset:16
	ds_read_b128 v[162:165], v131 offset:32
	ds_read_b128 v[76:79], v131 offset:48
	ds_read_b128 v[166:169], v130 offset:16368
	ds_read_b128 v[170:173], v130 offset:16384
	ds_read_b128 v[174:177], v130 offset:16400
	ds_read_b128 v[72:75], v130 offset:16416
	v_lshlrev_b32_e32 v86, 16, v80
	s_waitcnt lgkmcnt(3)
	v_sub_f32_e32 v85, v166, v88
	v_mul_f32_e32 v85, 0x3fb8aa3b, v85
	v_cndmask_b32_e64 v84, 0, v92, s[10:11]
	v_exp_f32_e32 v92, v85
	v_sub_f32_e32 v85, v88, v166
	v_and_b32_e32 v87, 0xffff0000, v80
	v_cndmask_b32_e64 v80, 0, v93, s[10:11]
	v_mul_f32_e32 v85, 0x3fb8aa3b, v85
	v_sub_f32_e32 v80, v89, v80
	v_exp_f32_e32 v166, v85
	v_mul_f32_e32 v85, 0x3fb8aa3b, v88
	v_mul_f32_e32 v80, 0x3fb8aa3b, v80
	v_exp_f32_e32 v178, v85
	v_exp_f32_e32 v85, v80
	v_sub_f32_e32 v80, v167, v89
	v_sub_f32_e32 v84, v88, v84
	v_mul_f32_e32 v80, 0x3fb8aa3b, v80
	v_mul_f32_e32 v84, 0x3fb8aa3b, v84
	v_exp_f32_e32 v93, v80
	v_sub_f32_e32 v80, v89, v167
	v_exp_f32_e32 v84, v84
	v_mul_f32_e32 v80, 0x3fb8aa3b, v80
	v_exp_f32_e32 v167, v80
	v_mul_f32_e32 v80, 0x3fb8aa3b, v89
	v_pk_add_f32 v[84:85], v[84:85], 1.0 op_sel_hi:[1,0] neg_lo:[1,0] neg_hi:[1,0]
	v_exp_f32_e32 v179, v80
	v_pk_mul_f32 v[84:85], v[84:85], v[92:93]
	v_pk_mul_f32 v[88:89], v[166:167], v[86:87]
	v_lshlrev_b32_e32 v166, 16, v81
	v_cndmask_b32_e64 v80, 0, v94, s[10:11]
	v_sub_f32_e32 v93, v90, v168
	v_and_b32_e32 v167, 0xffff0000, v81
	v_cndmask_b32_e64 v81, 0, v95, s[10:11]
	v_sub_f32_e32 v80, v90, v80
	v_mul_f32_e32 v93, 0x3fb8aa3b, v93
	v_sub_f32_e32 v81, v91, v81
	v_mul_f32_e32 v80, 0x3fb8aa3b, v80
	v_sub_f32_e32 v92, v168, v90
	v_exp_f32_e32 v94, v93
	v_mul_f32_e32 v81, 0x3fb8aa3b, v81
	v_sub_f32_e32 v93, v169, v91
	v_sub_f32_e32 v95, v91, v169
	v_exp_f32_e32 v80, v80
	v_mul_f32_e32 v92, 0x3fb8aa3b, v92
	v_exp_f32_e32 v81, v81
	v_mul_f32_e32 v93, 0x3fb8aa3b, v93
	v_mul_f32_e32 v95, 0x3fb8aa3b, v95
	v_exp_f32_e32 v92, v92
	v_exp_f32_e32 v93, v93
	v_exp_f32_e32 v95, v95
	v_pk_add_f32 v[80:81], v[80:81], 1.0 op_sel_hi:[1,0] neg_lo:[1,0] neg_hi:[1,0]
	v_mul_f32_e32 v90, 0x3fb8aa3b, v90
	v_mul_f32_e32 v91, 0x3fb8aa3b, v91
	v_pk_mul_f32 v[80:81], v[80:81], v[92:93]
	v_pk_mul_f32 v[92:93], v[94:95], v[166:167]
	v_cndmask_b32_e64 v95, 0, v158, s[10:11]
	v_exp_f32_e32 v90, v90
	v_exp_f32_e32 v91, v91
	v_sub_f32_e32 v95, v150, v95
	v_mul_f32_e32 v95, 0x3fb8aa3b, v95
	v_exp_f32_e32 v158, v95
	s_waitcnt lgkmcnt(2)
	v_sub_f32_e32 v95, v170, v150
	v_mul_f32_e32 v95, 0x3fb8aa3b, v95
	v_pk_mul_f32 v[90:91], v[90:91], v[166:167]
	v_exp_f32_e32 v166, v95
	v_sub_f32_e32 v95, v150, v170
	v_mul_f32_e32 v95, 0x3fb8aa3b, v95
	v_exp_f32_e32 v168, v95
	v_mul_f32_e32 v95, 0x3fb8aa3b, v150
	v_lshlrev_b32_e32 v94, 16, v82
	v_exp_f32_e32 v150, v95
	v_and_b32_e32 v95, 0xffff0000, v82
	v_cndmask_b32_e64 v82, 0, v159, s[10:11]
	v_sub_f32_e32 v82, v151, v82
	v_mul_f32_e32 v82, 0x3fb8aa3b, v82
	v_exp_f32_e32 v159, v82
	v_sub_f32_e32 v82, v171, v151
	v_mul_f32_e32 v82, 0x3fb8aa3b, v82
	v_exp_f32_e32 v167, v82
	v_sub_f32_e32 v82, v151, v171
	v_mul_f32_e32 v82, 0x3fb8aa3b, v82
	v_exp_f32_e32 v169, v82
	v_mul_f32_e32 v82, 0x3fb8aa3b, v151
	v_exp_f32_e32 v151, v82
	v_cndmask_b32_e64 v117, 0, v160, s[10:11]
	v_sub_f32_e32 v117, v152, v117
	v_pk_add_f32 v[158:159], v[158:159], 1.0 op_sel_hi:[1,0] neg_lo:[1,0] neg_hi:[1,0]
	v_mul_f32_e32 v117, 0x3fb8aa3b, v117
	v_pk_mul_f32 v[158:159], v[158:159], v[166:167]
	v_pk_mul_f32 v[166:167], v[168:169], v[94:95]
	v_pk_mul_f32 v[94:95], v[150:151], v[94:95]
	v_exp_f32_e32 v150, v117
	v_sub_f32_e32 v117, v172, v152
	v_mul_f32_e32 v117, 0x3fb8aa3b, v117
	v_exp_f32_e32 v160, v117
	v_sub_f32_e32 v117, v152, v172
	v_mul_f32_e32 v117, 0x3fb8aa3b, v117
	v_exp_f32_e32 v168, v117
	v_mul_f32_e32 v117, 0x3fb8aa3b, v152
	v_exp_f32_e32 v152, v117
	v_cndmask_b32_e64 v117, 0, v161, s[10:11]
	v_sub_f32_e32 v117, v153, v117
	v_mul_f32_e32 v117, 0x3fb8aa3b, v117
	v_exp_f32_e32 v151, v117
	v_sub_f32_e32 v117, v173, v153
	v_mul_f32_e32 v117, 0x3fb8aa3b, v117
	v_exp_f32_e32 v161, v117
	v_sub_f32_e32 v117, v153, v173
	v_mul_f32_e32 v117, 0x3fb8aa3b, v117
	v_exp_f32_e32 v169, v117
	v_mul_f32_e32 v117, 0x3fb8aa3b, v153
	v_exp_f32_e32 v153, v117
	v_lshlrev_b32_e32 v82, 16, v83
	v_and_b32_e32 v83, 0xffff0000, v83
	v_pk_add_f32 v[150:151], v[150:151], 1.0 op_sel_hi:[1,0] neg_lo:[1,0] neg_hi:[1,0]
	v_cndmask_b32_e64 v117, 0, v162, s[10:11]
	v_pk_mul_f32 v[150:151], v[150:151], v[160:161]
	v_pk_mul_f32 v[160:161], v[168:169], v[82:83]
	v_pk_mul_f32 v[82:83], v[152:153], v[82:83]
	v_lshlrev_b32_e32 v152, 16, v64
	v_and_b32_e32 v153, 0xffff0000, v64
	v_cndmask_b32_e64 v64, 0, v163, s[10:11]
	v_sub_f32_e32 v117, v154, v117
	v_sub_f32_e32 v64, v155, v64
	v_mul_f32_e32 v117, 0x3fb8aa3b, v117
	v_mul_f32_e32 v64, 0x3fb8aa3b, v64
	v_exp_f32_e32 v162, v117
	s_waitcnt lgkmcnt(1)
	v_sub_f32_e32 v117, v174, v154
	v_exp_f32_e32 v163, v64
	v_sub_f32_e32 v64, v175, v155
	v_mul_f32_e32 v117, 0x3fb8aa3b, v117
	v_mul_f32_e32 v64, 0x3fb8aa3b, v64
	v_exp_f32_e32 v168, v117
	v_sub_f32_e32 v117, v154, v174
	v_exp_f32_e32 v169, v64
	v_sub_f32_e32 v64, v155, v175
	v_mul_f32_e32 v117, 0x3fb8aa3b, v117
	v_mul_f32_e32 v64, 0x3fb8aa3b, v64
	v_exp_f32_e32 v170, v117
	v_mul_f32_e32 v117, 0x3fb8aa3b, v154
	v_exp_f32_e32 v171, v64
	v_mul_f32_e32 v64, 0x3fb8aa3b, v155
	v_exp_f32_e32 v154, v117
	v_exp_f32_e32 v155, v64
	v_cndmask_b32_e64 v117, 0, v164, s[10:11]
	v_sub_f32_e32 v117, v156, v117
	v_pk_add_f32 v[162:163], v[162:163], 1.0 op_sel_hi:[1,0] neg_lo:[1,0] neg_hi:[1,0]
	v_mul_f32_e32 v117, 0x3fb8aa3b, v117
	v_pk_mul_f32 v[162:163], v[162:163], v[168:169]
	v_pk_mul_f32 v[168:169], v[170:171], v[152:153]
	v_pk_mul_f32 v[152:153], v[154:155], v[152:153]
	v_exp_f32_e32 v154, v117
	v_sub_f32_e32 v117, v176, v156
	v_mul_f32_e32 v117, 0x3fb8aa3b, v117
	v_exp_f32_e32 v164, v117
	v_sub_f32_e32 v117, v156, v176
	v_mul_f32_e32 v117, 0x3fb8aa3b, v117
	v_exp_f32_e32 v170, v117
	v_mul_f32_e32 v117, 0x3fb8aa3b, v156
	v_exp_f32_e32 v156, v117
	v_cndmask_b32_e64 v117, 0, v165, s[10:11]
	v_sub_f32_e32 v117, v157, v117
	v_mul_f32_e32 v117, 0x3fb8aa3b, v117
	v_exp_f32_e32 v155, v117
	v_sub_f32_e32 v117, v177, v157
	v_mul_f32_e32 v117, 0x3fb8aa3b, v117
	v_exp_f32_e32 v165, v117
	v_sub_f32_e32 v117, v157, v177
	v_mul_f32_e32 v117, 0x3fb8aa3b, v117
	v_exp_f32_e32 v171, v117
	v_mul_f32_e32 v117, 0x3fb8aa3b, v157
	v_exp_f32_e32 v157, v117
	v_lshlrev_b32_e32 v64, 16, v65
	v_and_b32_e32 v65, 0xffff0000, v65
	v_pk_add_f32 v[154:155], v[154:155], 1.0 op_sel_hi:[1,0] neg_lo:[1,0] neg_hi:[1,0]
	v_pk_mul_f32 v[156:157], v[156:157], v[64:65]
	v_pk_mul_f32 v[154:155], v[154:155], v[164:165]
	v_pk_mul_f32 v[164:165], v[170:171], v[64:65]
	v_cndmask_b32_e64 v65, 0, v76, s[10:11]
	v_sub_f32_e32 v65, v68, v65
	v_mul_f32_e32 v65, 0x3fb8aa3b, v65
	v_exp_f32_e32 v76, v65
	s_waitcnt lgkmcnt(0)
	v_sub_f32_e32 v65, v72, v68
	v_mul_f32_e32 v65, 0x3fb8aa3b, v65
	v_exp_f32_e32 v170, v65
	v_sub_f32_e32 v65, v68, v72
	v_mul_f32_e32 v65, 0x3fb8aa3b, v65
	v_exp_f32_e32 v72, v65
	v_mul_f32_e32 v65, 0x3fb8aa3b, v68
	v_lshlrev_b32_e32 v64, 16, v66
	v_exp_f32_e32 v68, v65
	v_and_b32_e32 v65, 0xffff0000, v66
	v_cndmask_b32_e64 v66, 0, v77, s[10:11]
	v_sub_f32_e32 v66, v69, v66
	v_mul_f32_e32 v66, 0x3fb8aa3b, v66
	v_exp_f32_e32 v77, v66
	v_sub_f32_e32 v66, v73, v69
	v_mul_f32_e32 v66, 0x3fb8aa3b, v66
	v_exp_f32_e32 v171, v66
	v_sub_f32_e32 v66, v69, v73
	v_mul_f32_e32 v66, 0x3fb8aa3b, v66
	v_exp_f32_e32 v73, v66
	v_mul_f32_e32 v66, 0x3fb8aa3b, v69
	v_exp_f32_e32 v69, v66
	v_pk_add_f32 v[76:77], v[76:77], 1.0 op_sel_hi:[1,0] neg_lo:[1,0] neg_hi:[1,0]
	v_pk_mul_f32 v[86:87], v[178:179], v[86:87]
	v_pk_mul_f32 v[76:77], v[76:77], v[170:171]
	v_pk_mul_f32 v[170:171], v[72:73], v[64:65]
	v_pk_mul_f32 v[172:173], v[68:69], v[64:65]
	v_cndmask_b32_e64 v65, 0, v78, s[10:11]
	v_sub_f32_e32 v65, v70, v65
	v_mul_f32_e32 v65, 0x3fb8aa3b, v65
	v_exp_f32_e32 v66, v65
	v_sub_f32_e32 v65, v74, v70
	v_mul_f32_e32 v65, 0x3fb8aa3b, v65
	v_exp_f32_e32 v68, v65
	v_sub_f32_e32 v65, v70, v74
	v_mul_f32_e32 v65, 0x3fb8aa3b, v65
	v_exp_f32_e32 v72, v65
	v_mul_f32_e32 v65, 0x3fb8aa3b, v70
	v_lshlrev_b32_e32 v64, 16, v67
	v_exp_f32_e32 v70, v65
	v_and_b32_e32 v65, 0xffff0000, v67
	v_cndmask_b32_e64 v67, 0, v79, s[10:11]
	v_sub_f32_e32 v67, v71, v67
	v_mul_f32_e32 v67, 0x3fb8aa3b, v67
	v_sub_f32_e32 v69, v75, v71
	v_sub_f32_e32 v73, v71, v75
	v_exp_f32_e32 v67, v67
	v_mul_f32_e32 v69, 0x3fb8aa3b, v69
	v_mul_f32_e32 v73, 0x3fb8aa3b, v73
	v_mul_f32_e32 v71, 0x3fb8aa3b, v71
	v_exp_f32_e32 v69, v69
	v_exp_f32_e32 v73, v73
	v_exp_f32_e32 v71, v71
	v_pk_add_f32 v[66:67], v[66:67], 1.0 op_sel_hi:[1,0] neg_lo:[1,0] neg_hi:[1,0]
	v_cvt_pk_bf16_f32 v74, v94, v95
	v_pk_mul_f32 v[78:79], v[66:67], v[68:69]
	v_pk_mul_f32 v[174:175], v[72:73], v[64:65]
	v_pk_mul_f32 v[176:177], v[70:71], v[64:65]
	v_cvt_pk_bf16_f32 v64, v84, v85
	v_cvt_pk_bf16_f32 v65, v80, v81
	v_cvt_pk_bf16_f32 v66, v158, v159
	v_cvt_pk_bf16_f32 v67, v150, v151
	v_cvt_pk_bf16_f32 v68, v88, v89
	v_cvt_pk_bf16_f32 v69, v92, v93
	v_cvt_pk_bf16_f32 v70, v166, v167
	v_cvt_pk_bf16_f32 v71, v160, v161
	v_cvt_pk_bf16_f32 v72, v86, v87
	v_cvt_pk_bf16_f32 v73, v90, v91
	v_cvt_pk_bf16_f32 v75, v82, v83
	ds_write_b128 v132, v[64:67] offset:58368
	ds_write_b128 v133, v[68:71]
	ds_write_b128 v134, v[72:75]
	v_cvt_pk_bf16_f32 v64, v162, v163
	v_cvt_pk_bf16_f32 v65, v154, v155
	v_cvt_pk_bf16_f32 v66, v76, v77
	v_cvt_pk_bf16_f32 v67, v78, v79
	v_cvt_pk_bf16_f32 v68, v168, v169
	v_cvt_pk_bf16_f32 v69, v164, v165
	v_cvt_pk_bf16_f32 v70, v170, v171
	v_cvt_pk_bf16_f32 v71, v174, v175
	v_cvt_pk_bf16_f32 v72, v152, v153
	v_cvt_pk_bf16_f32 v73, v156, v157
	v_cvt_pk_bf16_f32 v74, v172, v173
	v_cvt_pk_bf16_f32 v75, v176, v177
	ds_write_b128 v132, v[64:67] offset:58384
	ds_write_b128 v133, v[68:71] offset:16
	ds_write_b128 v134, v[72:75] offset:16
	s_waitcnt lgkmcnt(0)
	s_barrier
	v_mov_b32_e32 v1, s99
	v_or_b32_e32 v0, v4, v110
	v_lshlrev_b64 v[0:1], 8, v[0:1]
	v_lshl_add_u64 v[0:1], v[102:103], 0, v[0:1]
	global_load_dwordx4 v[48:51], v[0:1], off
	global_load_dwordx4 v[52:55], v[0:1], off offset:64
	global_load_dwordx4 v[56:59], v[0:1], off offset:128
	global_load_dwordx4 v[60:63], v[0:1], off offset:192
	ds_read_b128 v[92:95], v136
	ds_read_b128 v[84:87], v136 offset:64
	ds_read_b128 v[76:79], v137
	ds_read_b128 v[72:75], v137 offset:64
	ds_read_b128 v[88:91], v136 offset:128
	ds_read_b128 v[80:83], v136 offset:192
	ds_read_b128 v[68:71], v137 offset:128
	ds_read_b128 v[64:67], v137 offset:192
	v_mov_b32_e32 v149, 0
	v_mov_b32_e32 v119, 0
	v_mov_b32_e32 v150, 0
	v_mov_b32_e32 v151, 0
	s_and_saveexec_b64 s[0:1], s[14:15]
	s_cbranch_execz .LBB0_981
	ds_read_b128 v[150:153], v142 offset:58368
	ds_read_b128 v[154:157], v142 offset:58432
	ds_read_b128 v[158:161], v142 offset:58496
	s_waitcnt lgkmcnt(2)
	v_mfma_f32_16x16x32_bf16 v[150:153], v[150:153], v[92:95], 0
	s_waitcnt lgkmcnt(1)
	v_mfma_f32_16x16x32_bf16 v[150:153], v[154:157], v[84:87], v[150:153]
	ds_read_b128 v[154:157], v142 offset:58560
	s_waitcnt lgkmcnt(1)
	v_mfma_f32_16x16x32_bf16 v[150:153], v[158:161], v[88:91], v[150:153]
	v_mov_b32_e32 v158, s69
	s_waitcnt lgkmcnt(0)
	v_mfma_f32_16x16x32_bf16 v[152:155], v[154:157], v[80:83], v[150:153]
	s_nop 7
	v_cndmask_b32_e64 v117, v152, v158, s[16:17]
	v_cndmask_b32_e64 v119, 0, v153, s[18:19]
	v_cndmask_b32_e64 v150, v154, 0, s[20:21]
	v_cndmask_b32_e64 v149, v117, v152, s[18:19]
	v_cndmask_b32_e64 v151, v155, 0, s[22:23]

.LBB0_985:
	s_or_b64 exec, exec, s[0:1]
	v_mov_b32_e32 v1, s99
	v_or_b32_e32 v0, v4, v112
	v_lshlrev_b64 v[0:1], 8, v[0:1]
	v_lshl_add_u64 v[0:1], v[102:103], 0, v[0:1]
	global_load_dwordx4 v[28:31], v[0:1], off
	global_load_dwordx4 v[24:27], v[0:1], off offset:64
	global_load_dwordx4 v[4:7], v[0:1], off offset:128
	s_nop 0
	global_load_dwordx4 v[0:3], v[0:1], off offset:192
	s_nop 0
	global_load_dwordx2 v[126:127], v[180:181], off
	global_load_dwordx2 v[124:125], v[180:181], off offset:32
	global_load_dwordx2 v[122:123], v[180:181], off offset:64
	global_load_dwordx2 v[120:121], v[180:181], off offset:96
	v_mov_b32_e32 v159, 0
	v_mov_b32_e32 v160, 0
	v_mov_b32_e32 v161, 0
	v_mov_b32_e32 v163, 0
	s_and_saveexec_b64 s[0:1], s[6:7]
	s_cbranch_execz .LBB0_987
	ds_read_b128 v[160:163], v143 offset:13056
	ds_read_b128 v[164:167], v143 offset:13120
	s_waitcnt lgkmcnt(1)
	v_mfma_f32_16x16x32_bf16 v[92:95], v[160:163], v[92:95], 0
	ds_read_b128 v[160:163], v143 offset:13184
	s_waitcnt lgkmcnt(1)
	v_mfma_f32_16x16x32_bf16 v[84:87], v[164:167], v[84:87], v[92:95]
	s_nop 4
	ds_read_b128 v[92:95], v143 offset:13248
	s_waitcnt lgkmcnt(1)
	v_mfma_f32_16x16x32_bf16 v[84:87], v[160:163], v[88:91], v[84:87]
	v_mov_b32_e32 v88, s69
	s_waitcnt lgkmcnt(0)
	v_mfma_f32_16x16x32_bf16 v[80:83], v[92:95], v[80:83], v[84:87]
	s_nop 7
	v_cndmask_b32_e64 v159, v80, v88, s[42:43]
	v_cndmask_b32_e64 v160, v81, 0, s[44:45]
	v_cndmask_b32_e64 v161, v82, 0, s[46:47]
	v_cndmask_b32_e64 v163, v83, 0, s[48:49]
